# P9 cross-attention scores: the single-quad ds_read -> wait -> MFMA round trip of the even-k half replaced by LDS reads running three tiles ahead through four rotating quads
# speedup vs baseline: 1.0000x; 1.0000x over previous
; #define LAS __attribute__((address_space(3)))
; #define MFMA32(a, b, c) __builtin_amdgcn_mfma_f32_32x32x16_bf16((a), (b), (c), 0, 0, 0)
; __device__ __forceinline__ void xa_item(int it, LAS unsigned char* lds, const bf16_t* XQ, const bf16_t* XK, bf16_t* PB, int tid, int wid, int lane) {
;     ...
;         if (wid < 4) {
; #pragma unroll 2
;             for (int ks = 0; ks < 8; ++ks) {
;                 const bf16x8 qv = *(const bf16x8*)(qp + c * 128 + 16 * ks);
; #pragma unroll
;                 for (int mt = 0; mt < 8; ++mt) st[mt] = MFMA32(*(const LAS bf16x8*)(KL + (32 * mt + x) * KS + 16 * ks + 8 * hi), qv, st[mt]);
;             }
.LBB0_1517:
	global_load_dwordx4 v[6:9], v[4:5], off offset:-32
	global_load_dwordx4 v[10:13], v[4:5], off
	s_mov_b32 s6, 0
	global_load_dwordx4 v[230:233], v[4:5], off offset:32
	global_load_dwordx4 v[234:237], v[4:5], off offset:64
	v_add_u32_e32 v3, s6, v195
	v_add_u32_e32 v185, s6, v194
	v_add_u32_e32 v210, s6, v193
	v_add_u32_e32 v218, s6, v192
	v_add_u32_e32 v226, s6, v191
	ds_read_b128 v[14:17], v3
	ds_read_b128 v[198:201], v3 offset:32
	ds_read_b128 v[238:241], v185
	ds_read_b128 v[202:205], v185 offset:32
	ds_read_b128 v[242:245], v3 offset:17408
	ds_read_b128 v[206:209], v3 offset:17440
	s_waitcnt vmcnt(3) lgkmcnt(5)
	v_mfma_f32_32x32x16_bf16 v[130:145], v[14:17], v[6:9], v[130:145]
	ds_read_b128 v[246:249], v210
	ds_read_b128 v[210:213], v210 offset:32
	s_waitcnt lgkmcnt(5)
	v_mfma_f32_32x32x16_bf16 v[114:129], v[238:241], v[6:9], v[114:129]
	ds_read_b128 v[14:17], v3 offset:34816
	ds_read_b128 v[214:217], v3 offset:34848
	s_waitcnt lgkmcnt(5)
	v_mfma_f32_32x32x16_bf16 v[98:113], v[242:245], v[6:9], v[98:113]
	ds_read_b128 v[238:241], v218
	ds_read_b128 v[218:221], v218 offset:32
	s_waitcnt lgkmcnt(5)
	v_mfma_f32_32x32x16_bf16 v[82:97], v[246:249], v[6:9], v[82:97]
	ds_read_b128 v[242:245], v3 offset:52224
	ds_read_b128 v[222:225], v3 offset:52256
	s_waitcnt lgkmcnt(5)
	v_mfma_f32_32x32x16_bf16 v[66:81], v[14:17], v[6:9], v[66:81]
	ds_read_b128 v[246:249], v226
	ds_read_b128 v[226:229], v226 offset:32
	s_waitcnt lgkmcnt(5)
	v_mfma_f32_32x32x16_bf16 v[50:65], v[238:241], v[6:9], v[50:65]
	s_waitcnt lgkmcnt(3)
	v_mfma_f32_32x32x16_bf16 v[34:49], v[242:245], v[6:9], v[34:49]
	s_waitcnt lgkmcnt(1)
	v_mfma_f32_32x32x16_bf16 v[18:33], v[246:249], v[6:9], v[18:33]
	s_waitcnt vmcnt(2)
	v_mfma_f32_32x32x16_bf16 v[130:145], v[198:201], v[10:13], v[130:145]
	v_mfma_f32_32x32x16_bf16 v[114:129], v[202:205], v[10:13], v[114:129]
	v_mfma_f32_32x32x16_bf16 v[98:113], v[206:209], v[10:13], v[98:113]
	v_mfma_f32_32x32x16_bf16 v[82:97], v[210:213], v[10:13], v[82:97]
	v_mfma_f32_32x32x16_bf16 v[66:81], v[214:217], v[10:13], v[66:81]
	v_mfma_f32_32x32x16_bf16 v[50:65], v[218:221], v[10:13], v[50:65]
	v_mfma_f32_32x32x16_bf16 v[34:49], v[222:225], v[10:13], v[34:49]
	s_waitcnt lgkmcnt(0)
	v_mfma_f32_32x32x16_bf16 v[18:33], v[226:229], v[10:13], v[18:33]
	s_mov_b32 s6, 64
	global_load_dwordx4 v[6:9], v[4:5], off offset:96
	global_load_dwordx4 v[10:13], v[4:5], off offset:128
	v_add_u32_e32 v3, s6, v195
	v_add_u32_e32 v185, s6, v194
	v_add_u32_e32 v210, s6, v193
	v_add_u32_e32 v218, s6, v192
	v_add_u32_e32 v226, s6, v191
	ds_read_b128 v[14:17], v3
	ds_read_b128 v[198:201], v3 offset:32
	ds_read_b128 v[238:241], v185
	ds_read_b128 v[202:205], v185 offset:32
	ds_read_b128 v[242:245], v3 offset:17408
	ds_read_b128 v[206:209], v3 offset:17440
	s_waitcnt vmcnt(3) lgkmcnt(5)
	v_mfma_f32_32x32x16_bf16 v[130:145], v[14:17], v[230:233], v[130:145]
	ds_read_b128 v[246:249], v210
	ds_read_b128 v[210:213], v210 offset:32
	s_waitcnt lgkmcnt(5)
	v_mfma_f32_32x32x16_bf16 v[114:129], v[238:241], v[230:233], v[114:129]
	ds_read_b128 v[14:17], v3 offset:34816
	ds_read_b128 v[214:217], v3 offset:34848
	s_waitcnt lgkmcnt(5)
	v_mfma_f32_32x32x16_bf16 v[98:113], v[242:245], v[230:233], v[98:113]
	ds_read_b128 v[238:241], v218
	ds_read_b128 v[218:221], v218 offset:32
	s_waitcnt lgkmcnt(5)
	v_mfma_f32_32x32x16_bf16 v[82:97], v[246:249], v[230:233], v[82:97]
	ds_read_b128 v[242:245], v3 offset:52224
	ds_read_b128 v[222:225], v3 offset:52256
	s_waitcnt lgkmcnt(5)
	v_mfma_f32_32x32x16_bf16 v[66:81], v[14:17], v[230:233], v[66:81]
	ds_read_b128 v[246:249], v226
	ds_read_b128 v[226:229], v226 offset:32
	s_waitcnt lgkmcnt(5)
	v_mfma_f32_32x32x16_bf16 v[50:65], v[238:241], v[230:233], v[50:65]
	s_waitcnt lgkmcnt(3)
	v_mfma_f32_32x32x16_bf16 v[34:49], v[242:245], v[230:233], v[34:49]
	s_waitcnt lgkmcnt(1)
	v_mfma_f32_32x32x16_bf16 v[18:33], v[246:249], v[230:233], v[18:33]
	s_waitcnt vmcnt(2)
	v_mfma_f32_32x32x16_bf16 v[130:145], v[198:201], v[234:237], v[130:145]
	v_mfma_f32_32x32x16_bf16 v[114:129], v[202:205], v[234:237], v[114:129]
	v_mfma_f32_32x32x16_bf16 v[98:113], v[206:209], v[234:237], v[98:113]
	v_mfma_f32_32x32x16_bf16 v[82:97], v[210:213], v[234:237], v[82:97]
	v_mfma_f32_32x32x16_bf16 v[66:81], v[214:217], v[234:237], v[66:81]
	v_mfma_f32_32x32x16_bf16 v[50:65], v[218:221], v[234:237], v[50:65]
	v_mfma_f32_32x32x16_bf16 v[34:49], v[222:225], v[234:237], v[34:49]
	s_waitcnt lgkmcnt(0)
; #define LAS __attribute__((address_space(3)))
; #define MFMA32(a, b, c) __builtin_amdgcn_mfma_f32_32x32x16_bf16((a), (b), (c), 0, 0, 0)
; __device__ __forceinline__ void xa_item(int it, LAS unsigned char* lds, const bf16_t* XQ, const bf16_t* XK, bf16_t* PB, int tid, int wid, int lane) {
;     ...
;         if (wid < 4) {
; #pragma unroll 2
;             for (int ks = 0; ks < 8; ++ks) {
;                 const bf16x8 qv = *(const bf16x8*)(qp + c * 128 + 16 * ks);
; #pragma unroll
;                 for (int mt = 0; mt < 8; ++mt) st[mt] = MFMA32(*(const LAS bf16x8*)(KL + (32 * mt + x) * KS + 16 * ks + 8 * hi), qv, st[mt]);
;             }
	v_mfma_f32_32x32x16_bf16 v[18:33], v[226:229], v[234:237], v[18:33]
	s_mov_b32 s6, 128
	global_load_dwordx4 v[230:233], v[4:5], off offset:160
	global_load_dwordx4 v[234:237], v[4:5], off offset:192
	v_add_u32_e32 v3, s6, v195
	v_add_u32_e32 v185, s6, v194
	v_add_u32_e32 v210, s6, v193
	v_add_u32_e32 v218, s6, v192
	v_add_u32_e32 v226, s6, v191
	ds_read_b128 v[14:17], v3
	ds_read_b128 v[198:201], v3 offset:32
	ds_read_b128 v[238:241], v185
	ds_read_b128 v[202:205], v185 offset:32
	ds_read_b128 v[242:245], v3 offset:17408
	ds_read_b128 v[206:209], v3 offset:17440
	s_waitcnt vmcnt(3) lgkmcnt(5)
	v_mfma_f32_32x32x16_bf16 v[130:145], v[14:17], v[6:9], v[130:145]
	ds_read_b128 v[246:249], v210
	ds_read_b128 v[210:213], v210 offset:32
	s_waitcnt lgkmcnt(5)
	v_mfma_f32_32x32x16_bf16 v[114:129], v[238:241], v[6:9], v[114:129]
	ds_read_b128 v[14:17], v3 offset:34816
	ds_read_b128 v[214:217], v3 offset:34848
	s_waitcnt lgkmcnt(5)
	v_mfma_f32_32x32x16_bf16 v[98:113], v[242:245], v[6:9], v[98:113]
	ds_read_b128 v[238:241], v218
	ds_read_b128 v[218:221], v218 offset:32
	s_waitcnt lgkmcnt(5)
	v_mfma_f32_32x32x16_bf16 v[82:97], v[246:249], v[6:9], v[82:97]
	ds_read_b128 v[242:245], v3 offset:52224
	ds_read_b128 v[222:225], v3 offset:52256
	s_waitcnt lgkmcnt(5)
	v_mfma_f32_32x32x16_bf16 v[66:81], v[14:17], v[6:9], v[66:81]
	ds_read_b128 v[246:249], v226
	ds_read_b128 v[226:229], v226 offset:32
	s_waitcnt lgkmcnt(5)
	v_mfma_f32_32x32x16_bf16 v[50:65], v[238:241], v[6:9], v[50:65]
	s_waitcnt lgkmcnt(3)
	v_mfma_f32_32x32x16_bf16 v[34:49], v[242:245], v[6:9], v[34:49]
	s_waitcnt lgkmcnt(1)
	v_mfma_f32_32x32x16_bf16 v[18:33], v[246:249], v[6:9], v[18:33]
	s_waitcnt vmcnt(2)
	v_mfma_f32_32x32x16_bf16 v[130:145], v[198:201], v[10:13], v[130:145]
	v_mfma_f32_32x32x16_bf16 v[114:129], v[202:205], v[10:13], v[114:129]
	v_mfma_f32_32x32x16_bf16 v[98:113], v[206:209], v[10:13], v[98:113]
	v_mfma_f32_32x32x16_bf16 v[82:97], v[210:213], v[10:13], v[82:97]
	v_mfma_f32_32x32x16_bf16 v[66:81], v[214:217], v[10:13], v[66:81]
	v_mfma_f32_32x32x16_bf16 v[50:65], v[218:221], v[10:13], v[50:65]
	v_mfma_f32_32x32x16_bf16 v[34:49], v[222:225], v[10:13], v[34:49]
	s_waitcnt lgkmcnt(0)
	v_mfma_f32_32x32x16_bf16 v[18:33], v[226:229], v[10:13], v[18:33]
	s_mov_b32 s6, 192
	v_add_u32_e32 v3, s6, v195
	v_add_u32_e32 v185, s6, v194
	v_add_u32_e32 v210, s6, v193
	v_add_u32_e32 v218, s6, v192
	v_add_u32_e32 v226, s6, v191
	ds_read_b128 v[14:17], v3
	ds_read_b128 v[198:201], v3 offset:32
	ds_read_b128 v[238:241], v185
	ds_read_b128 v[202:205], v185 offset:32
	ds_read_b128 v[242:245], v3 offset:17408
	ds_read_b128 v[206:209], v3 offset:17440
	s_waitcnt vmcnt(1) lgkmcnt(5)
	v_mfma_f32_32x32x16_bf16 v[130:145], v[14:17], v[230:233], v[130:145]
	ds_read_b128 v[246:249], v210
	ds_read_b128 v[210:213], v210 offset:32
	s_waitcnt lgkmcnt(5)
	v_mfma_f32_32x32x16_bf16 v[114:129], v[238:241], v[230:233], v[114:129]
	ds_read_b128 v[14:17], v3 offset:34816
	ds_read_b128 v[214:217], v3 offset:34848
	s_waitcnt lgkmcnt(5)
	v_mfma_f32_32x32x16_bf16 v[98:113], v[242:245], v[230:233], v[98:113]
	ds_read_b128 v[238:241], v218
	ds_read_b128 v[218:221], v218 offset:32
	s_waitcnt lgkmcnt(5)
	v_mfma_f32_32x32x16_bf16 v[82:97], v[246:249], v[230:233], v[82:97]
	ds_read_b128 v[242:245], v3 offset:52224
	ds_read_b128 v[222:225], v3 offset:52256
	s_waitcnt lgkmcnt(5)
	v_mfma_f32_32x32x16_bf16 v[66:81], v[14:17], v[230:233], v[66:81]
	ds_read_b128 v[246:249], v226
	ds_read_b128 v[226:229], v226 offset:32
	s_waitcnt lgkmcnt(5)
	v_mfma_f32_32x32x16_bf16 v[50:65], v[238:241], v[230:233], v[50:65]
	s_waitcnt lgkmcnt(3)
	v_mfma_f32_32x32x16_bf16 v[34:49], v[242:245], v[230:233], v[34:49]
	s_waitcnt lgkmcnt(1)
	v_mfma_f32_32x32x16_bf16 v[18:33], v[246:249], v[230:233], v[18:33]
	s_waitcnt vmcnt(0)
	v_mfma_f32_32x32x16_bf16 v[130:145], v[198:201], v[234:237], v[130:145]
	v_mfma_f32_32x32x16_bf16 v[114:129], v[202:205], v[234:237], v[114:129]
	v_mfma_f32_32x32x16_bf16 v[98:113], v[206:209], v[234:237], v[98:113]
	v_mfma_f32_32x32x16_bf16 v[82:97], v[210:213], v[234:237], v[82:97]
	v_mfma_f32_32x32x16_bf16 v[66:81], v[214:217], v[234:237], v[66:81]
	v_mfma_f32_32x32x16_bf16 v[50:65], v[218:221], v[234:237], v[50:65]
	v_mfma_f32_32x32x16_bf16 v[34:49], v[222:225], v[234:237], v[34:49]
	s_waitcnt lgkmcnt(0)
	v_mfma_f32_32x32x16_bf16 v[18:33], v[226:229], v[234:237], v[18:33]
	s_branch .LBB0_1512
